# G3 phase: workgroups 256..511 start ~17us late (half a tile) to desynchronize the two workgroups of a CU; on top of mixer 10us stagger
# baseline (speedup 1.0000x reference)
.LBB0_735:
	s_or_b64 exec, exec, s[6:7]
	v_readlane_b32 s6, v254, 14
	v_readlane_b32 s7, v254, 15
	v_readlane_b32 s15, v254, 18
	s_andn2_b64 vcc, exec, s[6:7]
	v_readlane_b32 s12, v254, 19
	s_mov_b32 s13, s15
	s_mov_b32 s14, s15
	s_barrier
	v_readlane_b32 s6, v254, 13
	s_cmpk_lt_u32 s6, 0x100
	s_cbranch_scc1 .Lg3_nodelay
	s_sleep 127
	s_sleep 127
	s_sleep 127
	s_sleep 127
	s_sleep 127
.Lg3_nodelay:
	s_cbranch_vccz .LBB0_771
